# E58: E52 plus exact vmcnt for the K/V staging writes in the diff loop's second tile copy (vmcnt(3) when this tile's loads were issued)
# baseline (speedup 1.0000x reference)
; #define SBAR() __builtin_amdgcn_sched_barrier(0)
; #define SWRITE(b, i) do { STG_T() const int _sv = VSTV(), _sk = LDSK(); *(u32x4*)(V_lds + (b) * SHM_V + _sv) = sr_[i].vs0; *(u32x4*)(V_lds + (b) * SHM_V + _sv + 8192) = sr_[i].vs1; \
;     _Pragma("unroll") for (int _p = 0; _p < NP; ++_p) *(u32x4*)(K_lds + (b) * KT + _sk + _p * 128) = sr_[i].ks[_p]; } while (0)
; #define SWAIT() do { if constexpr (SD == 2) { if constexpr (NP == 1) asm volatile("s_waitcnt vmcnt(3)" ::: "memory"); else asm volatile("s_waitcnt vmcnt(5)" ::: "memory"); } else asm volatile("s_waitcnt vmcnt(0)" ::: "memory"); } while (0)
; #define PVSM(VB, P0, P1, MN) do { if constexpr (MI) pv_mi(o, VB, pa0, pa1, pa2, pa3, P0); else pv_sm(o, VB, pa0, pa1, pa2, pa3, P0, P1, C, MN); } while (0)
; template <int D0> __device__ __forceinline__ void pv_one_mi(f32x16& od, int vb, bf16x8 pa0, bf16x8 pa1, bf16x8 pa2, bf16x8 pa3, f32x16& q0) {
;   const s16x4 l0 = tr_read<v_rd_off(D0, 0, 0)>(vb), h0 = tr_read<v_rd_off(D0, 0, 1)>(vb), l1 = tr_read<v_rd_off(D0, 1, 0)>(vb), h1 = tr_read<v_rd_off(D0, 1, 1)>(vb);
;   const s16x4 l2 = tr_read<v_rd_off(D0, 2, 0)>(vb), h2 = tr_read<v_rd_off(D0, 2, 1)>(vb), l3 = tr_read<v_rd_off(D0, 3, 0)>(vb), h3 = tr_read<v_rd_off(D0, 3, 1)>(vb);
;   asm volatile("s_waitcnt lgkmcnt(0)" ::: "memory"); SBAR();
;     ...
;   od = __builtin_amdgcn_mfma_f32_32x32x16_bf16(pa0, PK(l0, h0), od, 0, 0, 0);
;   od = __builtin_amdgcn_mfma_f32_32x32x16_bf16(pa1, PK(l1, h1), od, 0, 0, 0);
;   od = __builtin_amdgcn_mfma_f32_32x32x16_bf16(pa2, PK(l2, h2), od, 0, 0, 0);
;   od = __builtin_amdgcn_mfma_f32_32x32x16_bf16(pa3, PK(l3, h3), od, 0, 0, 0);
;     ...
; #pragma unroll
;   for (int r = 4 * D0; r < 4 * D0 + 4; ++r) q0[r] = __builtin_amdgcn_exp2f(q0[r]);
; }
; __device__ __forceinline__ void pv_mi(f32x16* o, int vb, bf16x8 pa0, bf16x8 pa1, bf16x8 pa2, bf16x8 pa3, f32x16& q0) {
;   pv_one_mi<0>(o[0], vb, pa0, pa1, pa2, pa3, q0); pv_one_mi<1>(o[1], vb, pa0, pa1, pa2, pa3, q0);
;   pv_one_mi<2>(o[2], vb, pa0, pa1, pa2, pa3, q0); pv_one_mi<3>(o[3], vb, pa0, pa1, pa2, pa3, q0);
; }
; template <int NQK, int SD, bool MI> ...
;     ...
;     PVSM(vb0 + rp * SHM_V, pA0, pA1, mnA);
;     SWAIT(); SWRITE(rn, SO);
.LBB0_1295:
	v_cvt_pk_bf16_f32 v250, v227, v229
	v_cvt_pk_bf16_f32 v251, v230, v233
	v_cvt_pk_bf16_f32 v252, v234, v237
	v_cvt_pk_bf16_f32 v253, v238, v241
	v_cvt_pk_bf16_f32 v228, v228, v231
	v_cvt_pk_bf16_f32 v229, v232, v235
	v_cvt_pk_bf16_f32 v230, v236, v239
	v_cvt_pk_bf16_f32 v231, v240, v242
	v_cvt_pk_bf16_f32 v232, v243, v244
	v_cvt_pk_bf16_f32 v233, v245, v115
	v_cvt_pk_bf16_f32 v234, v246, v247
	v_cvt_pk_bf16_f32 v235, v248, v119
	v_cvt_pk_bf16_f32 v116, v116, v117
	v_cvt_pk_bf16_f32 v117, v118, v120
	v_cvt_pk_bf16_f32 v118, v121, v122
	v_cvt_pk_bf16_f32 v119, v123, v124
	v_lshl_add_u32 v115, s15, 14, v214
	ds_read_b64_tr_b16 v[120:121], v115 offset:0
	ds_read_b64_tr_b16 v[122:123], v115 offset:0x800
	ds_read_b64_tr_b16 v[124:125], v115 offset:0x1000
	ds_read_b64_tr_b16 v[126:127], v115 offset:0x1800
	ds_read_b64_tr_b16 v[236:237], v115 offset:0x2000
	ds_read_b64_tr_b16 v[238:239], v115 offset:0x2800
	ds_read_b64_tr_b16 v[240:241], v115 offset:0x3000
	ds_read_b64_tr_b16 v[242:243], v115 offset:0x3800
	s_waitcnt lgkmcnt(6)
	s_nop 0
	v_mfma_f32_32x32x16_bf16 v[0:15], v[250:253], v[120:123], v[0:15]
	ds_read_b64_tr_b16 v[120:121], v115 offset:0x200
	ds_read_b64_tr_b16 v[122:123], v115 offset:0xa00
	s_waitcnt lgkmcnt(6)
	v_mfma_f32_32x32x16_bf16 v[0:15], v[228:231], v[124:127], v[0:15]
	ds_read_b64_tr_b16 v[124:125], v115 offset:0x1200
	ds_read_b64_tr_b16 v[126:127], v115 offset:0x1a00
	s_waitcnt lgkmcnt(6)
	v_mfma_f32_32x32x16_bf16 v[0:15], v[232:235], v[236:239], v[0:15]
	ds_read_b64_tr_b16 v[236:237], v115 offset:0x2200
	ds_read_b64_tr_b16 v[238:239], v115 offset:0x2a00
	s_waitcnt lgkmcnt(6)
	v_mfma_f32_32x32x16_bf16 v[0:15], v[116:119], v[240:243], v[0:15]
	ds_read_b64_tr_b16 v[240:241], v115 offset:0x3200
	ds_read_b64_tr_b16 v[242:243], v115 offset:0x3a00
	s_waitcnt lgkmcnt(6)
	v_mfma_f32_32x32x16_bf16 v[48:63], v[250:253], v[120:123], v[48:63]
	ds_read_b64_tr_b16 v[120:121], v115 offset:0x400
	ds_read_b64_tr_b16 v[122:123], v115 offset:0xc00
	s_waitcnt lgkmcnt(6)
	v_mfma_f32_32x32x16_bf16 v[48:63], v[228:231], v[124:127], v[48:63]
	ds_read_b64_tr_b16 v[124:125], v115 offset:0x1400
	ds_read_b64_tr_b16 v[126:127], v115 offset:0x1c00
	s_waitcnt lgkmcnt(6)
	v_mfma_f32_32x32x16_bf16 v[48:63], v[232:235], v[236:239], v[48:63]
	ds_read_b64_tr_b16 v[236:237], v115 offset:0x2400
	ds_read_b64_tr_b16 v[238:239], v115 offset:0x2c00
	s_waitcnt lgkmcnt(6)
	v_mfma_f32_32x32x16_bf16 v[48:63], v[116:119], v[240:243], v[48:63]
	ds_read_b64_tr_b16 v[240:241], v115 offset:0x3400
	ds_read_b64_tr_b16 v[242:243], v115 offset:0x3c00
	s_waitcnt lgkmcnt(6)
	v_mfma_f32_32x32x16_bf16 v[32:47], v[250:253], v[120:123], v[32:47]
	ds_read_b64_tr_b16 v[120:121], v115 offset:0x600
	ds_read_b64_tr_b16 v[122:123], v115 offset:0xe00
	s_waitcnt lgkmcnt(6)
	v_mfma_f32_32x32x16_bf16 v[32:47], v[228:231], v[124:127], v[32:47]
	ds_read_b64_tr_b16 v[124:125], v115 offset:0x1600
	ds_read_b64_tr_b16 v[126:127], v115 offset:0x1e00
	s_waitcnt lgkmcnt(6)
	v_mfma_f32_32x32x16_bf16 v[32:47], v[232:235], v[236:239], v[32:47]
	ds_read_b64_tr_b16 v[236:237], v115 offset:0x2600
	ds_read_b64_tr_b16 v[238:239], v115 offset:0x2e00
	s_waitcnt lgkmcnt(6)
	v_mfma_f32_32x32x16_bf16 v[32:47], v[116:119], v[240:243], v[32:47]
	ds_read_b64_tr_b16 v[240:241], v115 offset:0x3600
	ds_read_b64_tr_b16 v[242:243], v115 offset:0x3e00
	s_waitcnt lgkmcnt(0)
	v_mfma_f32_32x32x16_bf16 v[16:31], v[250:253], v[120:123], v[16:31]
	s_cmp_eq_u64 s[8:9], 0
	s_cbranch_scc1 .Ldb_iss
	s_waitcnt vmcnt(0)
	s_branch .Ldb_join

; #define SWRITE(b, i) do { STG_T() const int _sv = VSTV(), _sk = LDSK(); *(u32x4*)(V_lds + (b) * SHM_V + _sv) = sr_[i].vs0; *(u32x4*)(V_lds + (b) * SHM_V + _sv + 8192) = sr_[i].vs1; \
;     _Pragma("unroll") for (int _p = 0; _p < NP; ++_p) *(u32x4*)(K_lds + (b) * KT + _sk + _p * 128) = sr_[i].ks[_p]; } while (0)
; #define SWAIT() do { if constexpr (SD == 2) { if constexpr (NP == 1) asm volatile("s_waitcnt vmcnt(3)" ::: "memory"); else asm volatile("s_waitcnt vmcnt(5)" ::: "memory"); } else asm volatile("s_waitcnt vmcnt(0)" ::: "memory"); } while (0)
; #define RESC(a) do { if (__any((a) < 1.f)) { if (hi == 0) al_l[r32] = (a); asm volatile("s_waitcnt lgkmcnt(0)" ::: "memory"); \
;     _Pragma("unroll") for (int d = 0; d < 4; ++d) _Pragma("unroll") for (int r = 0; r < 16; ++r) o[d][r] *= al_l[crow(r, hi)]; } } while (0)
; #define ROT() do { const int _r = rp; rp = rc; rc = rn; rn = _r; } while (0)
; template <int NQK, int SD, bool MI> ...
;     ...
;     SWAIT(); SWRITE(rn, SO);
;     RESC(alA); __syncthreads(); ROT();
.Ldb_join:
	v_add_u32_e32 v115, s10, v218
	s_mul_i32 s17, s58, 0x2400
	ds_write_b128 v115, v[174:177]
	ds_write_b128 v115, v[178:181] offset:8192
	v_add_u32_e32 v115, s17, v219
	v_cmp_gt_f32_e32 vcc, 1.0, v112
	ds_write_b128 v115, v[182:185] offset:49152
	v_mfma_f32_32x32x16_bf16 v[16:31], v[228:231], v[124:127], v[16:31]
	v_mfma_f32_32x32x16_bf16 v[16:31], v[232:235], v[236:239], v[16:31]
	v_mfma_f32_32x32x16_bf16 v[16:31], v[116:119], v[240:243], v[16:31]
	s_cbranch_vccz .LBB0_1299
	s_and_saveexec_b64 s[10:11], s[6:7]
	ds_write_b32 v199, v112 offset:128
	s_or_b64 exec, exec, s[10:11]
	s_waitcnt lgkmcnt(0)
	v_add_u32_e32 v115, v191, v198
	ds_read_b128 v[116:119], v115 offset:224
	ds_read_b128 v[120:123], v115 offset:192
	ds_read_b128 v[124:127], v115 offset:160
	ds_read_b128 v[174:177], v115 offset:128
	s_waitcnt lgkmcnt(3)
	v_pk_mul_f32 v[12:13], v[12:13], v[116:117]
	s_waitcnt lgkmcnt(2)
	v_pk_mul_f32 v[8:9], v[8:9], v[120:121]
	s_waitcnt lgkmcnt(1)
	v_pk_mul_f32 v[4:5], v[4:5], v[124:125]
	v_pk_mul_f32 v[14:15], v[14:15], v[118:119]
	v_pk_mul_f32 v[10:11], v[10:11], v[122:123]
	v_pk_mul_f32 v[6:7], v[6:7], v[126:127]
	s_waitcnt lgkmcnt(0)
	v_pk_mul_f32 v[2:3], v[2:3], v[176:177]
	v_pk_mul_f32 v[0:1], v[0:1], v[174:175]
	v_pk_mul_f32 v[60:61], v[60:61], v[116:117]
	v_pk_mul_f32 v[56:57], v[56:57], v[120:121]
	v_pk_mul_f32 v[52:53], v[52:53], v[124:125]
	v_pk_mul_f32 v[62:63], v[62:63], v[118:119]
	v_pk_mul_f32 v[58:59], v[58:59], v[122:123]
	v_pk_mul_f32 v[54:55], v[54:55], v[126:127]
	v_pk_mul_f32 v[50:51], v[50:51], v[176:177]
	v_pk_mul_f32 v[48:49], v[48:49], v[174:175]
	v_pk_mul_f32 v[44:45], v[44:45], v[116:117]
	v_pk_mul_f32 v[40:41], v[40:41], v[120:121]
	v_pk_mul_f32 v[36:37], v[36:37], v[124:125]
	v_pk_mul_f32 v[46:47], v[46:47], v[118:119]
	v_pk_mul_f32 v[42:43], v[42:43], v[122:123]
	v_pk_mul_f32 v[38:39], v[38:39], v[126:127]
	v_pk_mul_f32 v[34:35], v[34:35], v[176:177]
	v_pk_mul_f32 v[32:33], v[32:33], v[174:175]
	v_pk_mul_f32 v[28:29], v[28:29], v[116:117]
	v_pk_mul_f32 v[24:25], v[24:25], v[120:121]
	v_pk_mul_f32 v[20:21], v[20:21], v[124:125]
	v_pk_mul_f32 v[30:31], v[30:31], v[118:119]
	v_pk_mul_f32 v[26:27], v[26:27], v[122:123]
	v_pk_mul_f32 v[22:23], v[22:23], v[126:127]
	v_pk_mul_f32 v[18:19], v[18:19], v[176:177]
	v_pk_mul_f32 v[16:17], v[16:17], v[174:175]
